# v23 + rwkv_post: token-shift mix vectors loaded with the current row (one load round trip per staging iteration instead of three); gate-GEMM B fragments (16 loads) issued up front instead of load->wai
# speedup vs baseline: 1.0106x; 1.0054x over previous
; #define LAS __attribute__((address_space(3)))
; DI f32x4 mma16(bf16x8 a, bf16x8 b, f32x4 c) { return __builtin_amdgcn_mfma_f32_16x16x32_bf16(a, b, c, 0, 0, 0); }
; DI void rwkv_post_item(KA a, const int l, LAS unsigned char* lds, const int tile) {
;     ...
;     const int hd = w >> 1, th = w & 1;
;     f32x4 accg[4][2];
; #pragma unroll
;     for (int ct = 0; ct < 4; ++ct) { accg[ct][0] = ZERO4; accg[ct][1] = ZERO4; }
;     const bf16* g2T = (const bf16*)(ws + WS_SMALL + l * SMALL_STRIDE + SM_G2T);
; #pragma unroll
;     for (int ks = 0; ks < 5; ++ks) {
;         bf16x8 af[2];
; #pragma unroll
;         for (int rt = 0; rt < 2; ++rt) af[rt] = *(const LAS bf16x8*)(Ag + (32 * th + 16 * rt + fr) * PG + ks * 32 + fq * 8);
; #pragma unroll
;         for (int ct = 0; ct < 4; ++ct) { const bf16x8 bg = *(const bf16x8*)(g2T + (size_t)(hd * 64 + ct * 16 + fr) * 192 + ks * 32 + fq * 8);
; #pragma unroll
;             for (int rt = 0; rt < 2; ++rt) accg[ct][rt] = mma16(bg, af[rt], accg[ct][rt]); }
;     }
.LBB0_980:
	s_or_b64 exec, exec, s[6:7]
	v_and_b32_e32 v0, 15, v5
	v_readlane_b32 s6, v254, 32
	v_lshrrev_b32_e32 v1, 1, v5
	v_bfe_u32 v60, v5, 4, 2
	s_add_u32 s6, s4, s6
	v_and_or_b32 v61, v1, 32, v0
	v_ashrrev_i32_e32 v1, 1, v5
	s_addc_u32 s7, s5, 0
	v_lshlrev_b32_e32 v192, 4, v60
	v_and_b32_e32 v62, 0xffffffc0, v1
	v_or_b32_e32 v34, v62, v0
	v_lshl_add_u64 v[0:1], s[6:7], 0, v[192:193]
	s_mov_b64 s[6:7], 0x310000
	v_lshl_add_u64 v[32:33], v[0:1], 0, s[6:7]
	s_movk_i32 s8, 0x180
	v_mul_u32_u24_e32 v0, 0x150, v61
	v_mad_i64_i32 v[52:53], s[6:7], v34, s8, v[32:33]
	v_or_b32_e32 v16, 16, v34
	v_or_b32_e32 v24, 32, v34
	v_or_b32_e32 v34, 48, v34
	v_add3_u32 v48, 0, v192, v0
	v_mad_i64_i32 v[54:55], s[6:7], v16, s8, v[32:33]
	v_mad_i64_i32 v[56:57], s[6:7], v24, s8, v[32:33]
	v_mad_i64_i32 v[58:59], s[6:7], v34, s8, v[32:33]
	s_waitcnt lgkmcnt(0)
	s_barrier
	ds_read_b128 v[0:3], v48
	ds_read_b128 v[4:7], v48 offset:5376
	global_load_dwordx4 v[8:11], v[52:53], off
	global_load_dwordx4 v[16:19], v[54:55], off
	global_load_dwordx4 v[24:27], v[56:57], off
	global_load_dwordx4 v[32:35], v[58:59], off
	global_load_dwordx4 v[120:123], v[52:53], off offset:64
	global_load_dwordx4 v[124:127], v[54:55], off offset:64
	global_load_dwordx4 v[128:131], v[56:57], off offset:64
	global_load_dwordx4 v[132:135], v[58:59], off offset:64
	global_load_dwordx4 v[136:139], v[52:53], off offset:128
	global_load_dwordx4 v[140:143], v[54:55], off offset:128
	global_load_dwordx4 v[144:147], v[56:57], off offset:128
	global_load_dwordx4 v[148:151], v[58:59], off offset:128
	global_load_dwordx4 v[152:155], v[52:53], off offset:192
	global_load_dwordx4 v[156:159], v[54:55], off offset:192
	global_load_dwordx4 v[160:163], v[56:57], off offset:192
	global_load_dwordx4 v[164:167], v[58:59], off offset:192
	global_load_dwordx4 v[168:171], v[52:53], off offset:256
	global_load_dwordx4 v[172:175], v[54:55], off offset:256
	global_load_dwordx4 v[176:179], v[56:57], off offset:256
	global_load_dwordx4 v[180:183], v[58:59], off offset:256
	s_add_u32 s10, s4, 0x18000000
	s_addc_u32 s11, s5, 0
	s_add_u32 s8, s4, 0x19000000
	s_addc_u32 s9, s5, 0
	v_readlane_b32 s16, v254, 33
	s_add_u32 s6, s4, 0x1a000000
	v_readlane_b32 s17, v254, 34
	s_addc_u32 s7, s5, 0
	s_lshl_b64 s[22:23], s[16:17], 2
	s_waitcnt vmcnt(19) lgkmcnt(1)
	v_mfma_f32_16x16x32_bf16 v[12:15], v[8:11], v[0:3], 0
	s_waitcnt lgkmcnt(0)
	v_mfma_f32_16x16x32_bf16 v[8:11], v[8:11], v[4:7], 0
	s_waitcnt vmcnt(18)
	v_mfma_f32_16x16x32_bf16 v[20:23], v[16:19], v[0:3], 0
	v_mfma_f32_16x16x32_bf16 v[16:19], v[16:19], v[4:7], 0
	s_waitcnt vmcnt(17)
	v_mfma_f32_16x16x32_bf16 v[28:31], v[24:27], v[0:3], 0
	v_mfma_f32_16x16x32_bf16 v[24:27], v[24:27], v[4:7], 0
	s_waitcnt vmcnt(16)
	v_mfma_f32_16x16x32_bf16 v[0:3], v[32:35], v[0:3], 0
	v_mfma_f32_16x16x32_bf16 v[4:7], v[32:35], v[4:7], 0
	ds_read_b128 v[32:35], v48 offset:64
	ds_read_b128 v[36:39], v48 offset:5440
	s_waitcnt vmcnt(0) lgkmcnt(1)
	v_mfma_f32_16x16x32_bf16 v[12:15], v[120:123], v[32:35], v[12:15]
	s_waitcnt lgkmcnt(0)
	v_mfma_f32_16x16x32_bf16 v[8:11], v[120:123], v[36:39], v[8:11]
	v_mfma_f32_16x16x32_bf16 v[20:23], v[124:127], v[32:35], v[20:23]
	v_mfma_f32_16x16x32_bf16 v[16:19], v[124:127], v[36:39], v[16:19]
	v_mfma_f32_16x16x32_bf16 v[28:31], v[128:131], v[32:35], v[28:31]
	v_mfma_f32_16x16x32_bf16 v[24:27], v[128:131], v[36:39], v[24:27]
	v_mfma_f32_16x16x32_bf16 v[0:3], v[132:135], v[32:35], v[0:3]
	v_mfma_f32_16x16x32_bf16 v[4:7], v[132:135], v[36:39], v[4:7]
	ds_read_b128 v[32:35], v48 offset:128
	ds_read_b128 v[36:39], v48 offset:5504
	s_waitcnt lgkmcnt(1)
	v_mfma_f32_16x16x32_bf16 v[12:15], v[136:139], v[32:35], v[12:15]
	s_waitcnt lgkmcnt(0)
	v_mfma_f32_16x16x32_bf16 v[8:11], v[136:139], v[36:39], v[8:11]
	v_mfma_f32_16x16x32_bf16 v[20:23], v[140:143], v[32:35], v[20:23]
	v_mfma_f32_16x16x32_bf16 v[16:19], v[140:143], v[36:39], v[16:19]
	v_mfma_f32_16x16x32_bf16 v[28:31], v[144:147], v[32:35], v[28:31]
	v_mfma_f32_16x16x32_bf16 v[24:27], v[144:147], v[36:39], v[24:27]
	v_mfma_f32_16x16x32_bf16 v[0:3], v[148:151], v[32:35], v[0:3]
	v_mfma_f32_16x16x32_bf16 v[4:7], v[148:151], v[36:39], v[4:7]
	ds_read_b128 v[32:35], v48 offset:192
	ds_read_b128 v[36:39], v48 offset:5568
	s_waitcnt lgkmcnt(1)
	v_mfma_f32_16x16x32_bf16 v[12:15], v[152:155], v[32:35], v[12:15]
	s_waitcnt lgkmcnt(0)
	v_mfma_f32_16x16x32_bf16 v[8:11], v[152:155], v[36:39], v[8:11]
	v_mfma_f32_16x16x32_bf16 v[20:23], v[156:159], v[32:35], v[20:23]
	v_mfma_f32_16x16x32_bf16 v[16:19], v[156:159], v[36:39], v[16:19]
	v_mfma_f32_16x16x32_bf16 v[44:47], v[160:163], v[32:35], v[28:31]
	v_mfma_f32_16x16x32_bf16 v[40:43], v[160:163], v[36:39], v[24:27]
	s_nop 2
	v_mfma_f32_16x16x32_bf16 v[0:3], v[164:167], v[32:35], v[0:3]
	v_mfma_f32_16x16x32_bf16 v[32:35], v[164:167], v[36:39], v[4:7]
	ds_read_b128 v[36:39], v48 offset:256
	ds_read_b128 v[48:51], v48 offset:5632
	s_nop 0
	s_waitcnt lgkmcnt(1)
	v_mfma_f32_16x16x32_bf16 v[28:31], v[168:171], v[36:39], v[12:15]
	s_waitcnt lgkmcnt(0)
	v_mfma_f32_16x16x32_bf16 v[12:15], v[168:171], v[48:51], v[8:11]
	v_mov_b64_e32 v[54:55], s[0:1]
	v_mfma_f32_16x16x32_bf16 v[24:27], v[172:175], v[36:39], v[20:23]
	v_mfma_f32_16x16x32_bf16 v[8:11], v[172:175], v[48:51], v[16:19]
	v_mfma_f32_16x16x32_bf16 v[20:23], v[176:179], v[36:39], v[44:47]
	v_mfma_f32_16x16x32_bf16 v[4:7], v[176:179], v[48:51], v[40:43]
	s_nop 2
	v_mfma_f32_16x16x32_bf16 v[16:19], v[180:183], v[36:39], v[0:3]
	s_load_dwordx4 s[12:15], s[2:3], 0x90
	s_load_dwordx2 s[20:21], s[2:3], 0xa0
	s_waitcnt lgkmcnt(0)
; DI void rwkv_post_item(KA a, const int l, LAS unsigned char* lds, const int tile) {
;     ...
;     for (int rt = 0; rt < 2; ++rt) { const int tk = t0 + 32 * th + 16 * rt + fr;
;         float y[4][4], sy = 0.f, srk = 0.f;
; #pragma unroll
;         for (int ct = 0; ct < 4; ++ct) { const int c4 = hd * 64 + ct * 16 + 4 * fq; const size_t ro = (size_t)tk * 256 + c4; const f32x4 rk4 = *(const f32x4*)(rkw + c4);
;             const v2u yy = *(const v2u*)(H + (size_t)tk * HP + C_RR + c4), r2 = *(const v2u*)(Rr + ro), k2 = *(const v2u*)(Rk + ro);
;             const float y_[4] = {bflo(yy.x), bfhi(yy.x), bflo(yy.y), bfhi(yy.y)}, r_[4] = {bflo(r2.x), bfhi(r2.x), bflo(r2.y), bfhi(r2.y)}, k_[4] = {bflo(k2.x), bfhi(k2.x), bflo(k2.y), bfhi(k2.y)};
; #pragma unroll
;             for (int j = 0; j < 4; ++j) { y[ct][j] = y_[j]; sy += y_[j]; srk += r_[j] * k_[j] * rk4[j]; } }
;         sy += __shfl_xor(sy, 16); sy += __shfl_xor(sy, 32); srk += __shfl_xor(srk, 16); srk += __shfl_xor(srk, 32);
	s_add_u32 s16, s12, s22
	v_mfma_f32_16x16x32_bf16 v[0:3], v[180:183], v[48:51], v[32:35]
	v_or_b32_e32 v50, s19, v61
	v_lshl_or_b32 v48, v60, 2, v62
	v_ashrrev_i32_e32 v51, 31, v50
	v_and_b32_e32 v33, 64, v238
	v_xor_b32_e32 v32, 16, v238
	v_add_u32_e32 v33, 64, v33
	v_cmp_lt_i32_e32 vcc, v32, v33
	s_movk_i32 s19, 0x1c00
	v_ashrrev_i32_e32 v49, 31, v48
	v_cndmask_b32_e32 v32, v238, v32, vcc
	v_lshlrev_b32_e32 v76, 2, v32
	v_xor_b32_e32 v32, 32, v238
	v_cmp_lt_i32_e32 vcc, v32, v33
	v_mad_i64_i32 v[34:35], s[0:1], v50, s19, v[54:55]
	s_nop 0
	v_cndmask_b32_e32 v32, v238, v32, vcc
	v_lshlrev_b32_e32 v67, 2, v32
	v_lshlrev_b64 v[32:33], 8, v[50:51]
	v_lshl_add_u64 v[56:57], v[32:33], 0, v[48:49]
	v_lshlrev_b64 v[40:41], 1, v[48:49]
	v_lshl_add_u64 v[38:39], v[34:35], 0, v[40:41]
	v_lshlrev_b64 v[34:35], 1, v[56:57]
	v_lshl_add_u64 v[56:57], s[10:11], 0, v[34:35]
	v_lshl_add_u64 v[34:35], s[8:9], 0, v[34:35]
	s_addc_u32 s17, s13, s23
	v_lshlrev_b64 v[36:37], 2, v[48:49]
	global_load_dwordx2 v[52:53], v[38:39], off offset:2080
	v_lshl_add_u64 v[42:43], s[16:17], 0, v[36:37]
	global_load_dwordx2 v[56:57], v[56:57], off
	s_add_u32 s12, s14, s22
	global_load_dwordx2 v[34:35], v[34:35], off
	s_addc_u32 s13, s15, s23
	global_load_dwordx4 v[44:47], v[42:43], off
	s_add_u32 s14, s20, s22
	s_addc_u32 s15, s21, s23
	s_mov_b64 s[16:17], 0x4000200
	s_add_i32 s18, s18, s76
	s_cmpk_lt_i32 s18, 0x200
	s_waitcnt vmcnt(3)
	v_lshlrev_b32_e32 v82, 16, v52
	v_and_b32_e32 v83, 0xffff0000, v52
	s_waitcnt vmcnt(2)
	v_lshlrev_b32_e32 v58, 16, v56
	v_and_b32_e32 v56, 0xffff0000, v56
	s_waitcnt vmcnt(1)
	v_lshlrev_b32_e32 v60, 16, v34
	v_and_b32_e32 v34, 0xffff0000, v34
	v_mul_f32_e32 v58, v58, v60
	v_lshlrev_b32_e32 v59, 16, v57
	v_lshlrev_b32_e32 v61, 16, v35
	s_waitcnt vmcnt(0)
	v_fma_f32 v60, v44, v58, 0
	v_mul_f32_e32 v34, v56, v34
	v_and_b32_e32 v57, 0xffff0000, v57
	v_and_b32_e32 v35, 0xffff0000, v35
	v_fmac_f32_e32 v60, v45, v34
	v_mul_f32_e32 v34, v59, v61
	v_or_b32_e32 v56, 16, v48
	v_fmac_f32_e32 v60, v46, v34
	v_mul_f32_e32 v34, v57, v35
	v_ashrrev_i32_e32 v57, 31, v56
	v_fmac_f32_e32 v60, v47, v34
	v_lshl_add_u64 v[34:35], v[32:33], 0, v[56:57]
	v_lshlrev_b64 v[34:35], 1, v[34:35]
	v_lshl_add_u64 v[58:59], s[10:11], 0, v[34:35]
	v_lshl_add_u64 v[34:35], s[8:9], 0, v[34:35]
	global_load_dwordx4 v[44:47], v[42:43], off offset:64
	global_load_dwordx2 v[62:63], v[38:39], off offset:2112
	v_lshlrev_b32_e32 v80, 16, v53
	global_load_dwordx2 v[58:59], v[58:59], off
	v_and_b32_e32 v81, 0xffff0000, v53
	global_load_dwordx2 v[34:35], v[34:35], off
	s_waitcnt vmcnt(2)
	v_lshlrev_b32_e32 v94, 16, v62
	v_and_b32_e32 v95, 0xffff0000, v62
	s_waitcnt vmcnt(1)
	v_lshlrev_b32_e32 v61, 16, v58
	v_and_b32_e32 v58, 0xffff0000, v58
	s_waitcnt vmcnt(0)
	v_lshlrev_b32_e32 v64, 16, v34
	v_and_b32_e32 v34, 0xffff0000, v34
	v_mul_f32_e32 v61, v61, v64
	v_fmac_f32_e32 v60, v44, v61
	v_mul_f32_e32 v34, v58, v34
	v_fmac_f32_e32 v60, v45, v34
	v_and_b32_e32 v45, 0xffff0000, v59
	v_lshlrev_b32_e32 v44, 16, v59
	v_and_b32_e32 v59, 0xffff0000, v35
	v_lshlrev_b32_e32 v58, 16, v35
	v_pk_mul_f32 v[34:35], v[44:45], v[58:59]
	v_or_b32_e32 v58, 32, v48
	v_pk_mul_f32 v[34:35], v[46:47], v[34:35]
	v_ashrrev_i32_e32 v59, 31, v58
	v_add_f32_e32 v34, v34, v60
	v_add_f32_e32 v66, v35, v34
	v_lshl_add_u64 v[34:35], v[32:33], 0, v[58:59]
	v_lshlrev_b64 v[34:35], 1, v[34:35]
	v_lshl_add_u64 v[60:61], s[10:11], 0, v[34:35]
	v_lshl_add_u64 v[34:35], s[8:9], 0, v[34:35]
	global_load_dwordx4 v[44:47], v[42:43], off offset:128
	global_load_dwordx2 v[64:65], v[38:39], off offset:2144
	v_lshlrev_b32_e32 v90, 16, v63
	global_load_dwordx2 v[60:61], v[60:61], off
	v_and_b32_e32 v91, 0xffff0000, v63
	global_load_dwordx2 v[34:35], v[34:35], off
	s_waitcnt vmcnt(2)
	v_lshlrev_b32_e32 v62, 16, v64
	v_and_b32_e32 v63, 0xffff0000, v64
	s_waitcnt vmcnt(1)
	v_and_b32_e32 v69, 0xffff0000, v60
	v_lshlrev_b32_e32 v68, 16, v60
	s_waitcnt vmcnt(0)
	v_and_b32_e32 v71, 0xffff0000, v34
	v_lshlrev_b32_e32 v70, 16, v34
	v_pk_mul_f32 v[68:69], v[68:69], v[70:71]
	v_lshlrev_b32_e32 v60, 16, v35
	v_pk_mul_f32 v[44:45], v[44:45], v[68:69]
	s_nop 0
	v_add_f32_e32 v34, v66, v44
	v_add_f32_e32 v66, v45, v34
	v_and_b32_e32 v45, 0xffff0000, v61
	v_lshlrev_b32_e32 v44, 16, v61
	v_and_b32_e32 v61, 0xffff0000, v35
	v_pk_mul_f32 v[34:35], v[44:45], v[60:61]
	v_or_b32_e32 v60, 48, v48
	v_pk_mul_f32 v[34:35], v[46:47], v[34:35]
	v_ashrrev_i32_e32 v61, 31, v60
	v_add_f32_e32 v34, v34, v66
	v_lshl_add_u64 v[44:45], v[32:33], 0, v[60:61]
	v_add_f32_e32 v66, v35, v34
	global_load_dwordx4 v[32:35], v[42:43], off offset:192
	global_load_dwordx2 v[72:73], v[38:39], off offset:2176
	v_lshlrev_b64 v[38:39], 1, v[44:45]
	v_lshl_add_u64 v[44:45], s[10:11], 0, v[38:39]
	v_lshl_add_u64 v[38:39], s[8:9], 0, v[38:39]
	global_load_dwordx2 v[44:45], v[44:45], off
	s_waitcnt vmcnt(1)
	v_and_b32_e32 v86, 0xffff0000, v72
	global_load_dwordx2 v[38:39], v[38:39], off
	v_lshlrev_b32_e32 v87, 16, v72
	v_and_b32_e32 v72, 0xffff0000, v65
	s_waitcnt vmcnt(1)
	v_and_b32_e32 v47, 0xffff0000, v44
	v_lshlrev_b32_e32 v46, 16, v44
	s_waitcnt vmcnt(0)
	v_and_b32_e32 v69, 0xffff0000, v38
	v_lshlrev_b32_e32 v68, 16, v38
	v_pk_mul_f32 v[46:47], v[46:47], v[68:69]
	v_lshlrev_b32_e32 v44, 16, v39
	v_pk_mul_f32 v[32:33], v[32:33], v[46:47]
	v_lshl_add_u64 v[46:47], s[14:15], 0, v[36:37]
	v_add_f32_e32 v32, v66, v32
	v_add_f32_e32 v38, v33, v32
	v_and_b32_e32 v33, 0xffff0000, v45
	v_lshlrev_b32_e32 v32, 16, v45
	v_and_b32_e32 v45, 0xffff0000, v39
	v_pk_mul_f32 v[32:33], v[32:33], v[44:45]
	v_lshl_add_u64 v[44:45], s[12:13], 0, v[36:37]
	v_pk_mul_f32 v[32:33], v[34:35], v[32:33]
	s_mov_b32 s12, 0xf800000
	v_add_f32_e32 v32, v32, v38
	v_add_f32_e32 v32, v33, v32
	ds_bpermute_b32 v33, v76, v32
	global_load_dwordx4 v[36:39], v[46:47], off
	s_waitcnt lgkmcnt(0)
; DI unsigned pk2(float lo, float hi) { const f32x2 v = {lo, hi}; const bf16x2_t b = __builtin_convertvector(v, bf16x2_t); return __builtin_bit_cast(unsigned, b); }
; DI void rwkv_post_item(KA a, const int l, LAS unsigned char* lds, const int tile) {
;     ...
;         sy += __shfl_xor(sy, 16); sy += __shfl_xor(sy, 32); srk += __shfl_xor(srk, 16); srk += __shfl_xor(srk, 32);
;         const float mean = sy * (1.f / 64.f); float q = 0.f;
; #pragma unroll
;         for (int ct = 0; ct < 4; ++ct)
; #pragma unroll
;             for (int j = 0; j < 4; ++j) { const float d = y[ct][j] - mean; q += d * d; }
;         q += __shfl_xor(q, 16); q += __shfl_xor(q, 32);
;         const float rstd = 1.f / sqrtf(q * (1.f / 64.f) + 64e-5f);
; #pragma unroll
;         for (int ct = 0; ct < 4; ++ct) { const int c4 = hd * 64 + ct * 16 + 4 * fq; const size_t ro = (size_t)tk * 256 + c4; const f32x4 lw = *(const f32x4*)(lnw + c4), lb = *(const f32x4*)(lnb + c4);
;             const v2u v2 = *(const v2u*)(Rv + ro); const float v_[4] = {bflo(v2.x), bfhi(v2.x), bflo(v2.y), bfhi(v2.y)}; float o[4];
; #pragma unroll
;             for (int j = 0; j < 4; ++j) o[j] = ((y[ct][j] - mean) * rstd * lw[j] + lb[j] + srk * v_[j]) * accg[ct][rt][j];
;             v2u p; p.x = pk2(o[0], o[1]); p.y = pk2(o[2], o[3]); *(v2u*)(act + (size_t)tk * D + 256 + c4) = p; }
	v_add_f32_e32 v32, v32, v33
	ds_bpermute_b32 v33, v67, v32
	s_waitcnt lgkmcnt(0)
	v_add_f32_e32 v66, v32, v33
	v_lshlrev_b64 v[32:33], 9, v[50:51]
	v_lshl_add_u64 v[70:71], s[6:7], 0, v[32:33]
	v_lshl_add_u64 v[70:71], v[70:71], 0, v[40:41]
	global_load_dwordx2 v[78:79], v[70:71], off
	global_load_dwordx2 v[52:53], v[70:71], off offset:32
	global_load_dwordx2 v[100:101], v[70:71], off offset:64
	v_lshlrev_b64 v[32:33], 11, v[50:51]
	v_add_f32_e32 v51, 0, v82
	v_add_f32_e32 v51, v51, v83
	v_add_f32_e32 v51, v51, v80
	v_add_f32_e32 v51, v51, v81
	v_add_f32_e32 v51, v51, v94
	v_add_f32_e32 v51, v51, v95
	v_add_f32_e32 v51, v51, v90
	v_lshl_add_u64 v[32:33], s[4:5], 0, v[32:33]
	v_add_f32_e32 v51, v51, v91
	v_lshl_add_u64 v[68:69], v[32:33], 0, s[16:17]
	global_load_dwordx4 v[32:35], v[44:45], off
	v_add_f32_e32 v51, v51, v62
	v_add_f32_e32 v51, v51, v63
	v_lshl_add_u64 v[88:89], v[68:69], 0, v[40:41]
	s_waitcnt vmcnt(3)
	v_lshlrev_b32_e32 v74, 16, v79
	v_and_b32_e32 v75, 0xffff0000, v79
	v_lshlrev_b32_e32 v84, 16, v78
	v_and_b32_e32 v85, 0xffff0000, v78
	v_and_b32_e32 v78, 0xffff0000, v73
	v_lshlrev_b32_e32 v79, 16, v73
	v_lshlrev_b32_e32 v73, 16, v65
	v_add_f32_e32 v51, v51, v73
	v_add_f32_e32 v51, v51, v72
	v_add_f32_e32 v51, v51, v87
	v_add_f32_e32 v51, v51, v86
	v_add_f32_e32 v51, v51, v79
	v_add_f32_e32 v51, v51, v78
	ds_bpermute_b32 v64, v76, v51
	s_waitcnt vmcnt(2)
	v_lshlrev_b32_e32 v96, 16, v52
	v_and_b32_e32 v97, 0xffff0000, v52
	v_lshlrev_b32_e32 v92, 16, v53
	v_and_b32_e32 v93, 0xffff0000, v53
	s_waitcnt lgkmcnt(0)
	v_add_f32_e32 v51, v51, v64
	ds_bpermute_b32 v64, v67, v51
	v_lshlrev_b64 v[52:53], 1, v[56:57]
	v_lshl_add_u64 v[98:99], v[68:69], 0, v[52:53]
	s_waitcnt lgkmcnt(0)
	v_add_f32_e32 v51, v51, v64
	v_mul_f32_e32 v102, 0x3c800000, v51
	v_pk_add_f32 v[82:83], v[82:83], v[102:103] op_sel_hi:[1,0] neg_lo:[0,1] neg_hi:[0,1]
	v_pk_add_f32 v[80:81], v[80:81], v[102:103] op_sel_hi:[1,0] neg_lo:[0,1] neg_hi:[0,1]
	v_pk_mul_f32 v[104:105], v[82:83], v[82:83]
	v_pk_mul_f32 v[106:107], v[80:81], v[80:81]
	v_add_f32_e32 v51, v104, v105
	v_pk_add_f32 v[94:95], v[94:95], v[102:103] op_sel_hi:[1,0] neg_lo:[0,1] neg_hi:[0,1]
	v_add_f32_e32 v51, v106, v51
	v_pk_mul_f32 v[108:109], v[94:95], v[94:95]
	v_add_f32_e32 v51, v107, v51
	v_pk_add_f32 v[90:91], v[90:91], v[102:103] op_sel_hi:[1,0] neg_lo:[0,1] neg_hi:[0,1]
	v_add_f32_e32 v51, v108, v51
	v_pk_mul_f32 v[110:111], v[90:91], v[90:91]
	v_add_f32_e32 v51, v109, v51
	v_pk_add_f32 v[112:113], v[62:63], v[102:103] op_sel_hi:[1,0] neg_lo:[0,1] neg_hi:[0,1]
	v_add_f32_e32 v51, v110, v51
	v_pk_mul_f32 v[114:115], v[112:113], v[112:113]
	v_add_f32_e32 v51, v111, v51
	v_pk_add_f32 v[116:117], v[72:73], v[102:103] op_sel_hi:[1,0] neg_lo:[0,1] neg_hi:[0,1]
	v_add_f32_e32 v51, v114, v51
	v_pk_mul_f32 v[72:73], v[116:117], v[116:117]
	v_add_f32_e32 v51, v115, v51
	v_pk_add_f32 v[64:65], v[86:87], v[102:103] op_sel_hi:[1,0] neg_lo:[0,1] neg_hi:[0,1]
	v_add_f32_e32 v51, v73, v51
	v_pk_mul_f32 v[86:87], v[64:65], v[64:65]
	v_add_f32_e32 v51, v72, v51
	v_pk_add_f32 v[62:63], v[78:79], v[102:103] op_sel_hi:[1,0] neg_lo:[0,1] neg_hi:[0,1]
	v_add_f32_e32 v51, v87, v51
	v_pk_mul_f32 v[78:79], v[62:63], v[62:63]
	v_add_f32_e32 v51, v86, v51
	v_add_f32_e32 v51, v79, v51
	v_add_f32_e32 v51, v78, v51
	ds_bpermute_b32 v72, v76, v51
	s_waitcnt lgkmcnt(0)
	v_add_f32_e32 v51, v51, v72
	ds_bpermute_b32 v72, v67, v51
	s_waitcnt lgkmcnt(0)
	v_add_f32_e32 v51, v51, v72
	v_fmamk_f32 v51, v51, 0x3c800000, v236
	v_cmp_gt_f32_e32 vcc, s12, v51
	v_mul_f32_e32 v72, 0x4f800000, v51
	s_nop 0
	v_cndmask_b32_e32 v51, v51, v72, vcc
	v_sqrt_f32_e32 v72, v51
	s_nop 0
	v_add_u32_e32 v73, -1, v72
	v_fma_f32 v77, -v73, v72, v51
	v_cmp_ge_f32_e64 s[0:1], 0, v77
	v_add_u32_e32 v77, 1, v72
	s_nop 0
	v_cndmask_b32_e64 v73, v72, v73, s[0:1]
	v_fma_f32 v72, -v77, v72, v51
	v_cmp_lt_f32_e64 s[0:1], 0, v72
	s_nop 1
	v_cndmask_b32_e64 v72, v73, v77, s[0:1]
	v_mul_f32_e32 v73, 0x37800000, v72
	v_cndmask_b32_e32 v72, v72, v73, vcc
	v_cmp_class_f32_e32 vcc, v51, v234
	s_nop 1
	v_cndmask_b32_e32 v51, v72, v51, vcc
	v_div_scale_f32 v72, s[0:1], v51, v51, 1.0
	v_rcp_f32_e32 v73, v72
	s_nop 0
	v_fma_f32 v77, -v72, v73, 1.0
	v_fmac_f32_e32 v73, v77, v73
	v_div_scale_f32 v77, vcc, 1.0, v51, 1.0
	v_mul_f32_e32 v78, v77, v73
	v_fma_f32 v79, -v72, v78, v77
	v_fmac_f32_e32 v78, v79, v73
	v_fma_f32 v72, -v72, v78, v77
	v_div_fmas_f32 v72, v72, v73, v78
	v_div_fixup_f32 v72, v72, v51, 1.0
	v_pk_mul_f32 v[78:79], v[82:83], v[72:73] op_sel_hi:[1,0]
	s_waitcnt vmcnt(0)
	v_pk_fma_f32 v[32:33], v[32:33], v[78:79], v[36:37]
	v_pk_mul_f32 v[36:37], v[94:95], v[72:73] op_sel_hi:[1,0]
	v_pk_fma_f32 v[32:33], v[66:67], v[84:85], v[32:33] op_sel_hi:[0,1,1]
	v_pk_mul_f32 v[28:29], v[28:29], v[32:33]
	v_pk_mul_f32 v[32:33], v[80:81], v[72:73] op_sel_hi:[1,0]
	v_cvt_pk_bf16_f32 v28, v28, v29
	v_pk_fma_f32 v[32:33], v[34:35], v[32:33], v[38:39]
	s_nop 0
	v_pk_fma_f32 v[32:33], v[66:67], v[74:75], v[32:33] op_sel_hi:[0,1,1]
	v_pk_mul_f32 v[30:31], v[30:31], v[32:33]
	s_nop 0
	v_cvt_pk_bf16_f32 v29, v30, v31
	global_store_dwordx2 v[88:89], v[28:29], off
	global_load_dwordx4 v[28:31], v[44:45], off offset:64
	s_nop 0
	global_load_dwordx4 v[32:35], v[46:47], off offset:64
	s_waitcnt vmcnt(0)
; DI unsigned pk2(float lo, float hi) { const f32x2 v = {lo, hi}; const bf16x2_t b = __builtin_convertvector(v, bf16x2_t); return __builtin_bit_cast(unsigned, b); }
; DI void rwkv_post_item(KA a, const int l, LAS unsigned char* lds, const int tile) {
;     ...
;     for (int rt = 0; rt < 2; ++rt) { const int tk = t0 + 32 * th + 16 * rt + fr;
;         float y[4][4], sy = 0.f, srk = 0.f;
; #pragma unroll
;         for (int ct = 0; ct < 4; ++ct) { const int c4 = hd * 64 + ct * 16 + 4 * fq; const size_t ro = (size_t)tk * 256 + c4; const f32x4 rk4 = *(const f32x4*)(rkw + c4);
;             const v2u yy = *(const v2u*)(H + (size_t)tk * HP + C_RR + c4), r2 = *(const v2u*)(Rr + ro), k2 = *(const v2u*)(Rk + ro);
;             const float y_[4] = {bflo(yy.x), bfhi(yy.x), bflo(yy.y), bfhi(yy.y)}, r_[4] = {bflo(r2.x), bfhi(r2.x), bflo(r2.y), bfhi(r2.y)}, k_[4] = {bflo(k2.x), bfhi(k2.x), bflo(k2.y), bfhi(k2.y)};
; #pragma unroll
;             for (int j = 0; j < 4; ++j) { y[ct][j] = y_[j]; sy += y_[j]; srk += r_[j] * k_[j] * rk4[j]; } }
;         sy += __shfl_xor(sy, 16); sy += __shfl_xor(sy, 32); srk += __shfl_xor(srk, 16); srk += __shfl_xor(srk, 32);
;         const float mean = sy * (1.f / 64.f); float q = 0.f;
; #pragma unroll
;         for (int ct = 0; ct < 4; ++ct)
; #pragma unroll
;             for (int j = 0; j < 4; ++j) { const float d = y[ct][j] - mean; q += d * d; }
;         q += __shfl_xor(q, 16); q += __shfl_xor(q, 32);
;         const float rstd = 1.f / sqrtf(q * (1.f / 64.f) + 64e-5f);
; #pragma unroll
;         for (int ct = 0; ct < 4; ++ct) { const int c4 = hd * 64 + ct * 16 + 4 * fq; const size_t ro = (size_t)tk * 256 + c4; const f32x4 lw = *(const f32x4*)(lnw + c4), lb = *(const f32x4*)(lnb + c4);
;             const v2u v2 = *(const v2u*)(Rv + ro); const float v_[4] = {bflo(v2.x), bfhi(v2.x), bflo(v2.y), bfhi(v2.y)}; float o[4];
; #pragma unroll
;             for (int j = 0; j < 4; ++j) o[j] = ((y[ct][j] - mean) * rstd * lw[j] + lb[j] + srk * v_[j]) * accg[ct][rt][j];
;             v2u p; p.x = pk2(o[0], o[1]); p.y = pk2(o[2], o[3]); *(v2u*)(act + (size_t)tk * D + 256 + c4) = p; }
	v_pk_fma_f32 v[28:29], v[28:29], v[36:37], v[32:33]
	s_nop 0
	v_pk_fma_f32 v[28:29], v[66:67], v[96:97], v[28:29] op_sel_hi:[0,1,1]
	v_pk_mul_f32 v[24:25], v[24:25], v[28:29]
	v_pk_mul_f32 v[28:29], v[90:91], v[72:73] op_sel_hi:[1,0]
	v_cvt_pk_bf16_f32 v24, v24, v25
	v_pk_fma_f32 v[28:29], v[30:31], v[28:29], v[34:35]
	v_pk_mul_f32 v[34:35], v[112:113], v[72:73] op_sel_hi:[1,0]
	v_pk_fma_f32 v[28:29], v[66:67], v[92:93], v[28:29] op_sel_hi:[0,1,1]
	v_pk_mul_f32 v[26:27], v[26:27], v[28:29]
	v_lshlrev_b32_e32 v32, 16, v100
	v_cvt_pk_bf16_f32 v25, v26, v27
	global_store_dwordx2 v[98:99], v[24:25], off
	global_load_dwordx4 v[24:27], v[44:45], off offset:128
	s_nop 0
	global_load_dwordx4 v[28:31], v[46:47], off offset:128
	v_and_b32_e32 v33, 0xffff0000, v100
	s_waitcnt vmcnt(0)
	v_pk_fma_f32 v[24:25], v[24:25], v[34:35], v[28:29]
	s_nop 0
	v_pk_fma_f32 v[24:25], v[66:67], v[32:33], v[24:25] op_sel_hi:[0,1,1]
	v_pk_mul_f32 v[28:29], v[116:117], v[72:73] op_sel_hi:[1,0]
	v_pk_mul_f32 v[20:21], v[20:21], v[24:25]
	v_lshlrev_b32_e32 v24, 16, v101
	v_and_b32_e32 v25, 0xffff0000, v101
	v_pk_fma_f32 v[26:27], v[26:27], v[28:29], v[30:31] op_sel:[0,1,0] op_sel_hi:[1,0,1]
	v_lshlrev_b64 v[28:29], 1, v[58:59]
	v_pk_fma_f32 v[24:25], v[66:67], v[24:25], v[26:27] op_sel_hi:[0,1,1]
	v_pk_mul_f32 v[22:23], v[22:23], v[24:25]
	v_cvt_pk_bf16_f32 v20, v20, v21
	v_cvt_pk_bf16_f32 v21, v22, v23
	v_lshl_add_u64 v[22:23], v[68:69], 0, v[28:29]
	global_store_dwordx2 v[22:23], v[20:21], off
	global_load_dwordx4 v[20:23], v[44:45], off offset:192
	s_nop 0
	global_load_dwordx4 v[24:27], v[46:47], off offset:192
	global_load_dwordx2 v[30:31], v[70:71], off offset:96
	v_pk_mul_f32 v[34:35], v[64:65], v[72:73] op_sel_hi:[1,0]
	s_waitcnt vmcnt(0)
	v_lshlrev_b32_e32 v32, 16, v30
	v_and_b32_e32 v33, 0xffff0000, v30
	v_pk_fma_f32 v[20:21], v[20:21], v[34:35], v[24:25] op_sel:[0,1,0] op_sel_hi:[1,0,1]
	v_pk_mul_f32 v[24:25], v[62:63], v[72:73] op_sel_hi:[1,0]
	v_pk_fma_f32 v[20:21], v[66:67], v[32:33], v[20:21] op_sel_hi:[0,1,1]
	v_pk_mul_f32 v[16:17], v[16:17], v[20:21]
	v_lshlrev_b32_e32 v20, 16, v31
	v_and_b32_e32 v21, 0xffff0000, v31
	v_pk_fma_f32 v[22:23], v[22:23], v[24:25], v[26:27] op_sel:[0,1,0] op_sel_hi:[1,0,1]
	v_lshlrev_b64 v[24:25], 1, v[60:61]
	v_pk_fma_f32 v[20:21], v[66:67], v[20:21], v[22:23] op_sel_hi:[0,1,1]
	v_pk_mul_f32 v[18:19], v[18:19], v[20:21]
	v_cvt_pk_bf16_f32 v16, v16, v17
	v_cvt_pk_bf16_f32 v17, v18, v19
	v_lshl_add_u64 v[18:19], v[68:69], 0, v[24:25]
	global_store_dwordx2 v[18:19], v[16:17], off
	v_or_b32_e32 v16, 16, v50
	v_ashrrev_i32_e32 v17, 31, v16
	v_lshlrev_b64 v[18:19], 8, v[16:17]
	v_lshl_add_u64 v[22:23], v[18:19], 0, v[48:49]
	v_mad_i64_i32 v[20:21], s[0:1], v16, s19, v[54:55]
	v_lshlrev_b64 v[22:23], 1, v[22:23]
	v_lshl_add_u64 v[20:21], v[20:21], 0, v[40:41]
	v_lshl_add_u64 v[26:27], s[10:11], 0, v[22:23]
	v_lshl_add_u64 v[22:23], s[8:9], 0, v[22:23]
	global_load_dwordx2 v[32:33], v[20:21], off offset:2080
	global_load_dwordx4 v[34:37], v[42:43], off
	s_nop 0
	global_load_dwordx2 v[26:27], v[26:27], off
	s_nop 0
	global_load_dwordx2 v[22:23], v[22:23], off
	s_waitcnt vmcnt(1)
	v_lshlrev_b32_e32 v30, 16, v26
	v_and_b32_e32 v26, 0xffff0000, v26
	s_waitcnt vmcnt(0)
	v_lshlrev_b32_e32 v38, 16, v22
	v_and_b32_e32 v22, 0xffff0000, v22
	v_mul_f32_e32 v30, v30, v38
	v_lshlrev_b32_e32 v31, 16, v27
	v_lshlrev_b32_e32 v39, 16, v23
	v_fma_f32 v48, v34, v30, 0
	v_mul_f32_e32 v22, v26, v22
	v_and_b32_e32 v27, 0xffff0000, v27
	v_and_b32_e32 v23, 0xffff0000, v23
	v_fmac_f32_e32 v48, v35, v22
	v_mul_f32_e32 v22, v31, v39
	v_fmac_f32_e32 v48, v36, v22
	v_mul_f32_e32 v22, v27, v23
	v_fmac_f32_e32 v48, v37, v22
	v_lshl_add_u64 v[22:23], v[18:19], 0, v[56:57]
	v_lshlrev_b64 v[22:23], 1, v[22:23]
	v_lshl_add_u64 v[26:27], s[10:11], 0, v[22:23]
	v_lshl_add_u64 v[22:23], s[8:9], 0, v[22:23]
	global_load_dwordx4 v[36:39], v[42:43], off offset:64
	global_load_dwordx2 v[34:35], v[20:21], off offset:2112
	v_lshlrev_b32_e32 v56, 16, v32
	global_load_dwordx2 v[26:27], v[26:27], off
	v_and_b32_e32 v57, 0xffff0000, v32
	global_load_dwordx2 v[22:23], v[22:23], off
	s_waitcnt vmcnt(2)
	v_lshlrev_b32_e32 v68, 16, v34
	v_and_b32_e32 v69, 0xffff0000, v34
	s_waitcnt vmcnt(1)
	v_lshlrev_b32_e32 v30, 16, v26
	v_and_b32_e32 v26, 0xffff0000, v26
	s_waitcnt vmcnt(0)
	v_lshlrev_b32_e32 v31, 16, v22
	v_and_b32_e32 v22, 0xffff0000, v22
	v_mul_f32_e32 v30, v30, v31
	v_fmac_f32_e32 v48, v36, v30
	v_mul_f32_e32 v22, v26, v22
	v_and_b32_e32 v31, 0xffff0000, v27
	v_lshlrev_b32_e32 v30, 16, v27
	v_and_b32_e32 v27, 0xffff0000, v23
	v_lshlrev_b32_e32 v26, 16, v23
	v_fmac_f32_e32 v48, v37, v22
	v_pk_mul_f32 v[22:23], v[30:31], v[26:27]
	v_lshlrev_b32_e32 v62, 16, v35
	v_pk_mul_f32 v[22:23], v[38:39], v[22:23]
	v_and_b32_e32 v63, 0xffff0000, v35
	v_add_f32_e32 v22, v22, v48
	v_add_f32_e32 v54, v23, v22
	v_lshl_add_u64 v[22:23], v[18:19], 0, v[58:59]
	v_lshlrev_b64 v[22:23], 1, v[22:23]
	v_lshl_add_u64 v[26:27], s[10:11], 0, v[22:23]
	v_lshl_add_u64 v[22:23], s[8:9], 0, v[22:23]
	global_load_dwordx4 v[48:51], v[42:43], off offset:128
	global_load_dwordx2 v[38:39], v[20:21], off offset:2144
	v_lshl_add_u64 v[18:19], v[18:19], 0, v[60:61]
	global_load_dwordx2 v[26:27], v[26:27], off
	v_lshlrev_b64 v[18:19], 1, v[18:19]
	global_load_dwordx2 v[22:23], v[22:23], off
	s_waitcnt vmcnt(2)
	v_lshlrev_b32_e32 v34, 16, v38
	v_and_b32_e32 v35, 0xffff0000, v38
	s_waitcnt vmcnt(1)
	v_and_b32_e32 v31, 0xffff0000, v26
	v_lshlrev_b32_e32 v30, 16, v26
	s_waitcnt vmcnt(0)
; DI void rwkv_post_item(KA a, const int l, LAS unsigned char* lds, const int tile) {
;     ...
;         for (int ct = 0; ct < 4; ++ct) { const int c4 = hd * 64 + ct * 16 + 4 * fq; const size_t ro = (size_t)tk * 256 + c4; const f32x4 rk4 = *(const f32x4*)(rkw + c4);
;             const v2u yy = *(const v2u*)(H + (size_t)tk * HP + C_RR + c4), r2 = *(const v2u*)(Rr + ro), k2 = *(const v2u*)(Rk + ro);
;             const float y_[4] = {bflo(yy.x), bfhi(yy.x), bflo(yy.y), bfhi(yy.y)}, r_[4] = {bflo(r2.x), bfhi(r2.x), bflo(r2.y), bfhi(r2.y)}, k_[4] = {bflo(k2.x), bfhi(k2.x), bflo(k2.y), bfhi(k2.y)};
; #pragma unroll
;             for (int j = 0; j < 4; ++j) { y[ct][j] = y_[j]; sy += y_[j]; srk += r_[j] * k_[j] * rk4[j]; } }
;         sy += __shfl_xor(sy, 16); sy += __shfl_xor(sy, 32); srk += __shfl_xor(srk, 16); srk += __shfl_xor(srk, 32);
;         const float mean = sy * (1.f / 64.f); float q = 0.f;
; #pragma unroll
;         for (int ct = 0; ct < 4; ++ct)
; #pragma unroll
;             for (int j = 0; j < 4; ++j) { const float d = y[ct][j] - mean; q += d * d; }
;         q += __shfl_xor(q, 16); q += __shfl_xor(q, 32);
	v_and_b32_e32 v37, 0xffff0000, v22
	v_lshlrev_b32_e32 v36, 16, v22
	v_pk_mul_f32 v[30:31], v[30:31], v[36:37]
	v_lshlrev_b32_e32 v26, 16, v23
	v_pk_mul_f32 v[30:31], v[48:49], v[30:31]
	s_nop 0
	v_add_f32_e32 v22, v54, v30
	v_add_f32_e32 v36, v31, v22
	v_and_b32_e32 v31, 0xffff0000, v27
	v_lshlrev_b32_e32 v30, 16, v27
	v_and_b32_e32 v27, 0xffff0000, v23
	v_pk_mul_f32 v[22:23], v[30:31], v[26:27]
	v_add_f32_e32 v31, 0, v56
	v_pk_mul_f32 v[22:23], v[50:51], v[22:23]
	global_load_dwordx4 v[48:51], v[42:43], off offset:192
	s_nop 0
	global_load_dwordx2 v[42:43], v[20:21], off offset:2176
	v_lshl_add_u64 v[20:21], s[10:11], 0, v[18:19]
	v_lshl_add_u64 v[18:19], s[8:9], 0, v[18:19]
	global_load_dwordx2 v[20:21], v[20:21], off
	v_add_f32_e32 v22, v22, v36
	global_load_dwordx2 v[18:19], v[18:19], off
	v_add_f32_e32 v30, v23, v22
	v_add_f32_e32 v31, v31, v57
	s_waitcnt vmcnt(2)
	v_and_b32_e32 v32, 0xffff0000, v43
	s_waitcnt vmcnt(1)
	v_and_b32_e32 v23, 0xffff0000, v20
	v_lshlrev_b32_e32 v22, 16, v20
	s_waitcnt vmcnt(0)
	v_and_b32_e32 v27, 0xffff0000, v18
	v_lshlrev_b32_e32 v26, 16, v18
	v_pk_mul_f32 v[22:23], v[22:23], v[26:27]
	v_lshlrev_b32_e32 v20, 16, v19
	v_pk_mul_f32 v[22:23], v[48:49], v[22:23]
	v_lshlrev_b32_e32 v48, 16, v33
	v_add_f32_e32 v18, v30, v22
	v_add_f32_e32 v26, v23, v18
	v_and_b32_e32 v23, 0xffff0000, v21
	v_lshlrev_b32_e32 v22, 16, v21
	v_and_b32_e32 v21, 0xffff0000, v19
	v_pk_mul_f32 v[18:19], v[22:23], v[20:21]
	v_and_b32_e32 v49, 0xffff0000, v33
	v_pk_mul_f32 v[18:19], v[50:51], v[18:19]
	v_add_f32_e32 v31, v31, v48
	v_add_f32_e32 v18, v18, v26
	v_add_f32_e32 v18, v19, v18
	ds_bpermute_b32 v19, v76, v18
	v_add_f32_e32 v31, v31, v49
	v_add_f32_e32 v31, v31, v68
	v_add_f32_e32 v31, v31, v69
	v_add_f32_e32 v31, v31, v62
	s_waitcnt lgkmcnt(0)
	v_add_f32_e32 v18, v18, v19
	ds_bpermute_b32 v19, v67, v18
	v_add_f32_e32 v31, v31, v63
	v_add_f32_e32 v31, v31, v34
	v_lshlrev_b32_e32 v33, 16, v43
	v_lshlrev_b32_e32 v43, 16, v39
	s_waitcnt lgkmcnt(0)
	v_add_f32_e32 v30, v18, v19
	v_lshlrev_b64 v[18:19], 9, v[16:17]
	v_lshl_add_u64 v[36:37], s[6:7], 0, v[18:19]
	v_lshlrev_b64 v[16:17], 11, v[16:17]
	v_lshl_add_u64 v[16:17], s[4:5], 0, v[16:17]
	v_lshl_add_u64 v[36:37], v[36:37], 0, v[40:41]
	v_lshl_add_u64 v[26:27], v[16:17], 0, s[16:17]
	global_load_dwordx4 v[16:19], v[44:45], off
	global_load_dwordx4 v[20:23], v[46:47], off
	global_load_dwordx2 v[54:55], v[36:37], off
	global_load_dwordx2 v[60:61], v[36:37], off offset:32
	v_add_f32_e32 v31, v31, v35
	v_add_f32_e32 v31, v31, v43
	v_lshl_add_u64 v[40:41], v[26:27], 0, v[40:41]
	v_lshl_add_u64 v[52:53], v[26:27], 0, v[52:53]
	s_waitcnt vmcnt(1)
	v_lshlrev_b32_e32 v50, 16, v55
	v_and_b32_e32 v51, 0xffff0000, v55
	v_lshlrev_b32_e32 v58, 16, v54
	v_and_b32_e32 v59, 0xffff0000, v54
	v_and_b32_e32 v54, 0xffff0000, v42
	v_lshlrev_b32_e32 v55, 16, v42
	v_and_b32_e32 v42, 0xffff0000, v39
	v_add_f32_e32 v31, v31, v42
	v_add_f32_e32 v31, v31, v55
	v_add_f32_e32 v31, v31, v54
	v_add_f32_e32 v31, v31, v33
	v_add_f32_e32 v31, v31, v32
	ds_bpermute_b32 v38, v76, v31
	s_waitcnt vmcnt(0)
	v_lshlrev_b32_e32 v64, 16, v61
	v_and_b32_e32 v65, 0xffff0000, v61
	v_lshlrev_b32_e32 v70, 16, v60
	v_and_b32_e32 v71, 0xffff0000, v60
	s_waitcnt lgkmcnt(0)
	v_add_f32_e32 v31, v31, v38
	ds_bpermute_b32 v38, v67, v31
	global_load_dwordx2 v[60:61], v[36:37], off offset:64
	s_waitcnt lgkmcnt(0)
	v_add_f32_e32 v31, v31, v38
	v_mul_f32_e32 v38, 0x3c800000, v31
	v_pk_add_f32 v[56:57], v[56:57], v[38:39] op_sel_hi:[1,0] neg_lo:[0,1] neg_hi:[0,1]
	v_pk_add_f32 v[48:49], v[48:49], v[38:39] op_sel_hi:[1,0] neg_lo:[0,1] neg_hi:[0,1]
	v_pk_mul_f32 v[72:73], v[56:57], v[56:57]
	v_pk_mul_f32 v[74:75], v[48:49], v[48:49]
	v_add_f32_e32 v31, v72, v73
	v_pk_add_f32 v[68:69], v[68:69], v[38:39] op_sel_hi:[1,0] neg_lo:[0,1] neg_hi:[0,1]
	v_add_f32_e32 v31, v74, v31
	v_pk_mul_f32 v[78:79], v[68:69], v[68:69]
	v_add_f32_e32 v31, v75, v31
	v_pk_add_f32 v[62:63], v[62:63], v[38:39] op_sel_hi:[1,0] neg_lo:[0,1] neg_hi:[0,1]
	v_add_f32_e32 v31, v78, v31
	v_pk_mul_f32 v[80:81], v[62:63], v[62:63]
	v_add_f32_e32 v31, v79, v31
	v_pk_add_f32 v[82:83], v[34:35], v[38:39] op_sel_hi:[1,0] neg_lo:[0,1] neg_hi:[0,1]
	v_add_f32_e32 v31, v80, v31
	v_pk_mul_f32 v[84:85], v[82:83], v[82:83]
	v_add_f32_e32 v31, v81, v31
	v_pk_add_f32 v[42:43], v[42:43], v[38:39] op_sel_hi:[1,0] neg_lo:[0,1] neg_hi:[0,1]
	v_add_f32_e32 v31, v84, v31
	v_pk_mul_f32 v[86:87], v[42:43], v[42:43]
	v_add_f32_e32 v31, v85, v31
	v_pk_add_f32 v[34:35], v[54:55], v[38:39] op_sel_hi:[1,0] neg_lo:[0,1] neg_hi:[0,1]
	v_add_f32_e32 v31, v87, v31
	v_pk_mul_f32 v[54:55], v[34:35], v[34:35]
	v_add_f32_e32 v31, v86, v31
	v_pk_add_f32 v[32:33], v[32:33], v[38:39] op_sel_hi:[1,0] neg_lo:[0,1] neg_hi:[0,1]
	v_add_f32_e32 v31, v55, v31
	v_pk_mul_f32 v[38:39], v[32:33], v[32:33]
	v_add_f32_e32 v31, v54, v31
	v_add_f32_e32 v31, v39, v31
	v_add_f32_e32 v31, v38, v31
	ds_bpermute_b32 v38, v76, v31
	s_waitcnt lgkmcnt(0)
; DI unsigned pk2(float lo, float hi) { const f32x2 v = {lo, hi}; const bf16x2_t b = __builtin_convertvector(v, bf16x2_t); return __builtin_bit_cast(unsigned, b); }
; DI void rwkv_post_item(KA a, const int l, LAS unsigned char* lds, const int tile) {
;     ...
;         const float rstd = 1.f / sqrtf(q * (1.f / 64.f) + 64e-5f);
; #pragma unroll
;         for (int ct = 0; ct < 4; ++ct) { const int c4 = hd * 64 + ct * 16 + 4 * fq; const size_t ro = (size_t)tk * 256 + c4; const f32x4 lw = *(const f32x4*)(lnw + c4), lb = *(const f32x4*)(lnb + c4);
;             const v2u v2 = *(const v2u*)(Rv + ro); const float v_[4] = {bflo(v2.x), bfhi(v2.x), bflo(v2.y), bfhi(v2.y)}; float o[4];
; #pragma unroll
;             for (int j = 0; j < 4; ++j) o[j] = ((y[ct][j] - mean) * rstd * lw[j] + lb[j] + srk * v_[j]) * accg[ct][rt][j];
;             v2u p; p.x = pk2(o[0], o[1]); p.y = pk2(o[2], o[3]); *(v2u*)(act + (size_t)tk * D + 256 + c4) = p; }
	v_add_f32_e32 v31, v31, v38
	ds_bpermute_b32 v38, v67, v31
	s_waitcnt lgkmcnt(0)
	v_add_f32_e32 v31, v31, v38
	v_fmamk_f32 v31, v31, 0x3c800000, v236
	v_cmp_gt_f32_e32 vcc, s12, v31
	v_mul_f32_e32 v38, 0x4f800000, v31
	s_nop 0
	v_cndmask_b32_e32 v31, v31, v38, vcc
	v_sqrt_f32_e32 v38, v31
	s_nop 0
	v_add_u32_e32 v39, -1, v38
	v_fma_f32 v54, -v39, v38, v31
	v_cmp_ge_f32_e64 s[0:1], 0, v54
	v_add_u32_e32 v54, 1, v38
	s_nop 0
	v_cndmask_b32_e64 v39, v38, v39, s[0:1]
	v_fma_f32 v38, -v54, v38, v31
	v_cmp_lt_f32_e64 s[0:1], 0, v38
	s_nop 1
	v_cndmask_b32_e64 v38, v39, v54, s[0:1]
	v_mul_f32_e32 v39, 0x37800000, v38
	v_cndmask_b32_e32 v38, v38, v39, vcc
	v_cmp_class_f32_e32 vcc, v31, v234
	s_nop 1
	v_cndmask_b32_e32 v31, v38, v31, vcc
	v_div_scale_f32 v38, s[0:1], v31, v31, 1.0
	v_rcp_f32_e32 v39, v38
	s_nop 0
	v_fma_f32 v54, -v38, v39, 1.0
	v_fmac_f32_e32 v39, v54, v39
	v_div_scale_f32 v54, vcc, 1.0, v31, 1.0
	v_mul_f32_e32 v55, v54, v39
	v_fma_f32 v66, -v38, v55, v54
	v_fmac_f32_e32 v55, v66, v39
	v_fma_f32 v38, -v38, v55, v54
	v_div_fmas_f32 v38, v38, v39, v55
	v_div_fixup_f32 v38, v38, v31, 1.0
	v_pk_mul_f32 v[54:55], v[56:57], v[38:39] op_sel_hi:[1,0]
	s_nop 0
	v_pk_fma_f32 v[16:17], v[16:17], v[54:55], v[20:21]
	v_pk_mul_f32 v[20:21], v[68:69], v[38:39] op_sel_hi:[1,0]
	v_pk_fma_f32 v[16:17], v[30:31], v[58:59], v[16:17] op_sel_hi:[0,1,1]
	v_pk_mul_f32 v[12:13], v[12:13], v[16:17]
	v_pk_mul_f32 v[16:17], v[48:49], v[38:39] op_sel_hi:[1,0]
	v_cvt_pk_bf16_f32 v12, v12, v13
	v_pk_fma_f32 v[16:17], v[18:19], v[16:17], v[22:23]
	s_nop 0
	v_pk_fma_f32 v[16:17], v[30:31], v[50:51], v[16:17] op_sel_hi:[0,1,1]
	v_pk_mul_f32 v[14:15], v[14:15], v[16:17]
	s_nop 0
	v_cvt_pk_bf16_f32 v13, v14, v15
	global_store_dwordx2 v[40:41], v[12:13], off
	global_load_dwordx4 v[12:15], v[44:45], off offset:64
	s_nop 0
	global_load_dwordx4 v[16:19], v[46:47], off offset:64
	s_waitcnt vmcnt(0)
	v_pk_fma_f32 v[12:13], v[12:13], v[20:21], v[16:17]
	s_nop 0
	v_pk_fma_f32 v[12:13], v[30:31], v[70:71], v[12:13] op_sel_hi:[0,1,1]
	v_pk_mul_f32 v[8:9], v[8:9], v[12:13]
	v_pk_mul_f32 v[12:13], v[62:63], v[38:39] op_sel_hi:[1,0]
	v_cvt_pk_bf16_f32 v8, v8, v9
	v_pk_fma_f32 v[12:13], v[14:15], v[12:13], v[18:19]
	v_pk_mul_f32 v[18:19], v[82:83], v[38:39] op_sel_hi:[1,0]
	v_pk_fma_f32 v[12:13], v[30:31], v[64:65], v[12:13] op_sel_hi:[0,1,1]
	v_pk_mul_f32 v[10:11], v[10:11], v[12:13]
	v_lshlrev_b32_e32 v16, 16, v60
	v_cvt_pk_bf16_f32 v9, v10, v11
	global_store_dwordx2 v[52:53], v[8:9], off
	global_load_dwordx4 v[8:11], v[44:45], off offset:128
	s_nop 0
	global_load_dwordx4 v[12:15], v[46:47], off offset:128
	v_and_b32_e32 v17, 0xffff0000, v60
	s_waitcnt vmcnt(0)
	v_pk_fma_f32 v[8:9], v[8:9], v[18:19], v[12:13]
	s_nop 0
	v_pk_fma_f32 v[8:9], v[30:31], v[16:17], v[8:9] op_sel_hi:[0,1,1]
	v_pk_mul_f32 v[12:13], v[42:43], v[38:39] op_sel_hi:[1,0]
	v_pk_mul_f32 v[4:5], v[4:5], v[8:9]
	v_lshlrev_b32_e32 v8, 16, v61
	v_and_b32_e32 v9, 0xffff0000, v61
	v_pk_fma_f32 v[10:11], v[10:11], v[12:13], v[14:15] op_sel:[0,1,0] op_sel_hi:[1,0,1]
	v_cvt_pk_bf16_f32 v4, v4, v5
	v_pk_fma_f32 v[8:9], v[30:31], v[8:9], v[10:11] op_sel_hi:[0,1,1]
	v_pk_mul_f32 v[6:7], v[6:7], v[8:9]
	v_pk_mul_f32 v[16:17], v[34:35], v[38:39] op_sel_hi:[1,0]
	v_cvt_pk_bf16_f32 v5, v6, v7
	v_lshl_add_u64 v[6:7], v[26:27], 0, v[28:29]
	global_store_dwordx2 v[6:7], v[4:5], off
	global_load_dwordx4 v[4:7], v[44:45], off offset:192
	s_nop 0
	global_load_dwordx4 v[8:11], v[46:47], off offset:192
	global_load_dwordx2 v[12:13], v[36:37], off offset:96
	s_waitcnt vmcnt(1)
	v_pk_fma_f32 v[4:5], v[4:5], v[16:17], v[8:9] op_sel:[0,1,0] op_sel_hi:[1,0,1]
	s_waitcnt vmcnt(0)
	v_lshlrev_b32_e32 v14, 16, v12
	v_and_b32_e32 v15, 0xffff0000, v12
	v_pk_fma_f32 v[4:5], v[30:31], v[14:15], v[4:5] op_sel_hi:[0,1,1]
	v_pk_mul_f32 v[8:9], v[32:33], v[38:39] op_sel_hi:[1,0]
	v_pk_mul_f32 v[0:1], v[0:1], v[4:5]
	v_lshlrev_b32_e32 v4, 16, v13
	v_and_b32_e32 v5, 0xffff0000, v13
	v_pk_fma_f32 v[6:7], v[6:7], v[8:9], v[10:11] op_sel:[0,1,0] op_sel_hi:[1,0,1]
	v_cvt_pk_bf16_f32 v0, v0, v1
	v_pk_fma_f32 v[4:5], v[30:31], v[4:5], v[6:7] op_sel_hi:[0,1,1]
	v_pk_mul_f32 v[2:3], v[2:3], v[4:5]
	s_nop 0
	v_cvt_pk_bf16_f32 v1, v2, v3
	v_lshl_add_u64 v[2:3], v[26:27], 0, v[24:25]
	global_store_dwordx2 v[2:3], v[0:1], off
	s_cbranch_scc0 .LBB0_986

; #define LAS __attribute__((address_space(3)))
; DI float sigmoidf_(float x) { return __builtin_amdgcn_rcpf(1.f + __expf(-x)); }
; DI void unpack8(const v4u u, float (&f)[8]) { f[0] = bflo(u.x); f[1] = bfhi(u.x); f[2] = bflo(u.y); f[3] = bfhi(u.y); f[4] = bflo(u.z); f[5] = bfhi(u.z); f[6] = bflo(u.w); f[7] = bfhi(u.w); }
; DI v4u pack8(const float (&f)[8]) { v4u o; o.x = pk2(f[0], f[1]); o.y = pk2(f[2], f[3]); o.z = pk2(f[4], f[5]); o.w = pk2(f[6], f[7]); return o; }
; DI void rwkv_post_item(KA a, const int l, LAS unsigned char* lds, const int tile) {
;     ...
;     for (int idx = tid; idx < 64 * 20; idx += NTHR) { const int tk = idx / 20, c0 = (idx % 20) * 8, t = t0 + tk; const bool first = (t & (SEQ - 1)) == 0;
;         const bf16* hr = H + (size_t)t * HP; float cu[8], pv[8], o[8];
;         unpack8(*(const v4u*)(hr + C_RGL + c0), cu); if (first) { for (int e = 0; e < 8; ++e) pv[e] = 0.f; } else unpack8(*(const v4u*)(hr - HP + C_RGL + c0), pv);
; #pragma unroll
;         for (int e = 0; e < 8; ++e) o[e] = sigmoidf_(cu[e] + (pv[e] - cu[e]) * mu[896 + c0 + e]);
;         *(LAS v4u*)(Ag + tk * PG + c0) = pack8(o); }
.LBB0_983:
	s_or_b64 exec, exec, s[12:13]
	s_waitcnt vmcnt(0)
	v_lshlrev_b32_e32 v21, 16, v0
	v_and_b32_e32 v22, 0xffff0000, v0
	v_lshlrev_b32_e32 v23, 16, v1
	v_and_b32_e32 v24, 0xffff0000, v1
	v_lshlrev_b32_e32 v25, 16, v2
	v_and_b32_e32 v26, 0xffff0000, v2
	v_lshlrev_b32_e32 v27, 16, v3
	v_and_b32_e32 v28, 0xffff0000, v3
	v_sub_f32_e32 v16, v16, v25
	v_sub_f32_e32 v20, v20, v21
	v_sub_f32_e32 v19, v19, v22
	v_sub_f32_e32 v18, v18, v23
	v_sub_f32_e32 v17, v17, v24
	s_movk_i32 s12, 0x2ff
	v_cmp_lt_i32_e32 vcc, s12, v11
	v_add_u32_e32 v4, 0x1000, v4
	s_or_b64 s[10:11], vcc, s[10:11]
	v_fmac_f32_e32 v25, v16, v120
	v_mul_f32_e32 v0, 0xbfb8aa3b, v25
	v_exp_f32_e32 v0, v0
	v_fmac_f32_e32 v21, v124, v20
	v_fmac_f32_e32 v22, v19, v125
	v_fmac_f32_e32 v23, v18, v126
	v_add_f32_e32 v0, 1.0, v0
	v_rcp_f32_e32 v16, v0
	v_sub_f32_e32 v0, v15, v26
	v_fmac_f32_e32 v26, v0, v121
	v_mul_f32_e32 v0, 0xbfb8aa3b, v26
	v_exp_f32_e32 v0, v0
	v_fmac_f32_e32 v24, v17, v127
	v_mul_f32_e32 v6, 0xbfb8aa3b, v21
	v_mul_f32_e32 v7, 0xbfb8aa3b, v22
	v_add_f32_e32 v0, 1.0, v0
	v_rcp_f32_e32 v15, v0
	v_sub_f32_e32 v0, v14, v27
	v_fmac_f32_e32 v27, v0, v122
	v_mul_f32_e32 v0, 0xbfb8aa3b, v27
	v_exp_f32_e32 v0, v0
	v_mul_f32_e32 v8, 0xbfb8aa3b, v23
	v_mul_f32_e32 v9, 0xbfb8aa3b, v24
	v_exp_f32_e32 v6, v6
	v_add_f32_e32 v0, 1.0, v0
	v_rcp_f32_e32 v14, v0
	v_sub_f32_e32 v0, v13, v28
	v_fmac_f32_e32 v28, v0, v123
	v_mul_f32_e32 v0, 0xbfb8aa3b, v28
	v_exp_f32_e32 v7, v7
	v_exp_f32_e32 v8, v8
	v_exp_f32_e32 v9, v9
	v_exp_f32_e32 v0, v0
	v_add_f32_e32 v6, 1.0, v6
	v_add_f32_e32 v7, 1.0, v7
	v_add_f32_e32 v8, 1.0, v8
	v_add_f32_e32 v9, 1.0, v9
	v_add_f32_e32 v0, 1.0, v0
	v_rcp_f32_e32 v6, v6
	v_rcp_f32_e32 v7, v7
	v_rcp_f32_e32 v8, v8
	v_rcp_f32_e32 v9, v9
	v_rcp_f32_e32 v3, v0
	v_cvt_pk_bf16_f32 v0, v6, v7
	v_cvt_pk_bf16_f32 v2, v16, v15
	v_cvt_pk_bf16_f32 v1, v8, v9
	v_cvt_pk_bf16_f32 v3, v14, v3
	v_lshl_add_u32 v6, v12, 4, v10
	ds_write_b128 v6, v[0:3]
	v_add_u32_e32 v0, 0x200, v11
	v_add_u32_e32 v10, 0x2000, v10
	v_mov_b32_e32 v11, v0
	s_andn2_b64 exec, exec, s[10:11]
	s_cbranch_execz .LBB0_980
.LBB0_984:
	s_mov_b32 s12, 0x66666667
	v_mul_hi_i32 v0, v11, s12
	v_lshrrev_b32_e32 v1, 31, v0
	v_ashrrev_i32_e32 v0, 3, v0
	s_waitcnt vmcnt(3)
	v_add_u32_e32 v12, v0, v1
	s_movk_i32 s12, 0xff60
	v_mad_u64_u32 v[6:7], s[12:13], v12, s12, v[4:5]
	v_add_u32_e32 v13, s19, v12
	v_mov_b64_e32 v[0:1], s[0:1]
	s_movk_i32 s12, 0x1c00
	v_mad_i64_i32 v[0:1], s[12:13], v13, s12, v[0:1]
	v_ashrrev_i32_e32 v7, 31, v6
	v_lshl_add_u64 v[8:9], v[6:7], 1, v[0:1]
	global_load_dwordx4 v[0:3], v[8:9], off offset:3872
	v_lshl_add_u64 v[118:119], v[6:7], 2, s[8:9]
	global_load_dwordx4 v[120:123], v[118:119], off offset:3600
	global_load_dwordx4 v[124:127], v[118:119], off offset:3584
	v_and_b32_e32 v13, 0x7ff, v13
	v_cmp_ne_u32_e32 vcc, 0, v13
	v_mov_b32_e32 v20, 0
	v_mov_b32_e32 v19, 0
	v_mov_b32_e32 v18, 0
	v_mov_b32_e32 v17, 0
	v_mov_b32_e32 v16, 0
	s_waitcnt vmcnt(3)
	v_mov_b32_e32 v15, 0
	v_mov_b32_e32 v14, 0
	v_mov_b32_e32 v13, 0
	s_and_saveexec_b64 s[12:13], vcc
	s_cbranch_execz .LBB0_983
	global_load_dwordx4 v[22:25], v[8:9], off offset:-3296
	s_waitcnt vmcnt(0)
	v_lshlrev_b32_e32 v20, 16, v22
	v_and_b32_e32 v19, 0xffff0000, v22
	v_lshlrev_b32_e32 v18, 16, v23
	v_and_b32_e32 v17, 0xffff0000, v23
	v_lshlrev_b32_e32 v16, 16, v24
	v_and_b32_e32 v15, 0xffff0000, v24
	v_lshlrev_b32_e32 v14, 16, v25
	v_and_b32_e32 v13, 0xffff0000, v25
	s_branch .LBB0_983
